# experiment: nt policy also on the decode KV-cache stream loads
# speedup vs baseline: 1.0252x; 1.0085x over previous
.Ldc_nopf:
	s_ashr_i32 s7, s6, 31
	s_lshl_b64 s[6:7], s[6:7], 19
	s_add_u32 s12, s80, s6
	s_addc_u32 s13, s81, s7
	s_and_b32 s13, s13, 0xffff
	buffer_load_dwordx4 v[42:45], v247, s[12:15], 0 offen nt
	buffer_load_dwordx4 v[46:49], v247, s[12:15], s43 offen nt
	buffer_load_dwordx4 v[50:53], v247, s[12:15], s46 offen nt
	buffer_load_dwordx4 v[54:57], v247, s[12:15], s47 offen nt
	buffer_load_dwordx4 v[58:61], v247, s[12:15], s16 offen nt
	s_movk_i32 s16, 0x4800
	buffer_load_dwordx4 v[62:65], v247, s[12:15], s16 offen nt
	s_mov_b32 s16, 0x8800
	buffer_load_dwordx4 v[66:69], v247, s[12:15], s16 offen nt
	s_mov_b32 s16, 0xc800
	buffer_load_dwordx4 v[70:73], v247, s[12:15], s16 offen nt
	s_mov_b32 s16, 0x10800
	s_waitcnt vmcnt(7)
	v_cvt_pk_bf16_f32 v42, v42, v43
	v_cvt_pk_bf16_f32 v43, v44, v45
	ds_write_b64 v249, v[42:43]
	s_waitcnt vmcnt(6)
	v_cvt_pk_bf16_f32 v42, v46, v47
	v_cvt_pk_bf16_f32 v43, v48, v49
	ds_write_b64 v249, v[42:43] offset:576
	s_waitcnt vmcnt(5)
	v_cvt_pk_bf16_f32 v42, v50, v51
	v_cvt_pk_bf16_f32 v43, v52, v53
	ds_write_b64 v249, v[42:43] offset:1152
	s_waitcnt vmcnt(4)
	v_cvt_pk_bf16_f32 v42, v54, v55
	v_cvt_pk_bf16_f32 v43, v56, v57
	ds_write_b64 v249, v[42:43] offset:1728
	s_waitcnt vmcnt(3)
	v_cvt_pk_bf16_f32 v42, v58, v59
	v_cvt_pk_bf16_f32 v43, v60, v61
	ds_write_b64 v249, v[42:43] offset:2304
	s_waitcnt vmcnt(2)
	v_cvt_pk_bf16_f32 v42, v62, v63
	v_cvt_pk_bf16_f32 v43, v64, v65
	ds_write_b64 v249, v[42:43] offset:2880
	s_waitcnt vmcnt(1)
	v_cvt_pk_bf16_f32 v42, v66, v67
	v_cvt_pk_bf16_f32 v43, v68, v69
	ds_write_b64 v249, v[42:43] offset:3456
	s_waitcnt vmcnt(0)
	v_cvt_pk_bf16_f32 v74, v70, v71
	v_cvt_pk_bf16_f32 v75, v72, v73
	buffer_load_dwordx4 v[42:45], v247, s[12:15], s48 offen nt
	buffer_load_dwordx4 v[46:49], v247, s[12:15], s49 offen nt
	buffer_load_dwordx4 v[50:53], v247, s[12:15], s50 offen nt
	buffer_load_dwordx4 v[54:57], v247, s[12:15], s51 offen nt
	buffer_load_dwordx4 v[58:61], v247, s[12:15], s16 offen nt
	s_mov_b32 s16, 0x14800
	buffer_load_dwordx4 v[62:65], v247, s[12:15], s16 offen nt
	s_mov_b32 s16, 0x18800
	buffer_load_dwordx4 v[66:69], v247, s[12:15], s16 offen nt
	s_mov_b32 s16, 0x1c800
	buffer_load_dwordx4 v[70:73], v247, s[12:15], s16 offen nt
	ds_write_b64 v249, v[74:75] offset:4032
	s_waitcnt lgkmcnt(0)
	ds_read_b128 v[74:77], v250
	ds_read_b128 v[78:81], v250 offset:64
	s_waitcnt lgkmcnt(1)
	v_mfma_f32_16x16x32_bf16 v[74:77], v[74:77], v[2:5], 0
	ds_read_b128 v[82:85], v250 offset:2304
	s_add_u32 s16, s82, s6
	s_addc_u32 s6, s83, s7
	s_waitcnt lgkmcnt(1)
	v_mfma_f32_16x16x32_bf16 v[74:77], v[78:81], v[6:9], v[74:77]
	ds_read_b128 v[78:81], v250 offset:2368
	s_waitcnt lgkmcnt(1)
	v_mfma_f32_16x16x32_bf16 v[82:85], v[82:85], v[2:5], 0
	s_waitcnt lgkmcnt(0)
	v_mfma_f32_16x16x32_bf16 v[78:81], v[78:81], v[6:9], v[82:85]
	s_nop 7
	v_cndmask_b32_e64 v205, v81, v77, s[2:3]
	v_cndmask_b32_e64 v204, v80, v76, s[2:3]
	v_cndmask_b32_e64 v207, v79, v75, s[2:3]
	v_cndmask_b32_e64 v206, v78, v74, s[2:3]
	s_waitcnt vmcnt(7)
	v_cvt_pk_bf16_f32 v42, v42, v43
	v_cvt_pk_bf16_f32 v43, v44, v45
	ds_write_b64 v249, v[42:43] offset:4608
	s_waitcnt vmcnt(6)
	v_cvt_pk_bf16_f32 v42, v46, v47
	v_cvt_pk_bf16_f32 v43, v48, v49
	ds_write_b64 v249, v[42:43] offset:5184
	s_waitcnt vmcnt(5)
	v_cvt_pk_bf16_f32 v42, v50, v51
	v_cvt_pk_bf16_f32 v43, v52, v53
	ds_write_b64 v249, v[42:43] offset:5760
	s_waitcnt vmcnt(4)
	v_cvt_pk_bf16_f32 v42, v54, v55
	v_cvt_pk_bf16_f32 v43, v56, v57
	ds_write_b64 v249, v[42:43] offset:6336
	s_waitcnt vmcnt(3)
	v_cvt_pk_bf16_f32 v42, v58, v59
	v_cvt_pk_bf16_f32 v43, v60, v61
	ds_write_b64 v249, v[42:43] offset:6912
	s_waitcnt vmcnt(2)
	v_cvt_pk_bf16_f32 v42, v62, v63
	v_cvt_pk_bf16_f32 v43, v64, v65
	ds_write_b64 v249, v[42:43] offset:7488
	s_waitcnt vmcnt(1)
	v_cvt_pk_bf16_f32 v42, v66, v67
	v_cvt_pk_bf16_f32 v43, v68, v69
	s_mov_b32 s7, 0x20800
	ds_write_b64 v249, v[42:43] offset:8064
	s_waitcnt vmcnt(0)
	v_cvt_pk_bf16_f32 v74, v70, v71
	v_cvt_pk_bf16_f32 v75, v72, v73
	buffer_load_dwordx4 v[42:45], v247, s[12:15], s15 offen nt
	buffer_load_dwordx4 v[46:49], v247, s[12:15], s52 offen nt
	buffer_load_dwordx4 v[50:53], v247, s[12:15], s53 offen nt
	buffer_load_dwordx4 v[54:57], v247, s[12:15], s54 offen nt
	buffer_load_dwordx4 v[58:61], v247, s[12:15], s7 offen nt
	s_mov_b32 s7, 0x24800
	buffer_load_dwordx4 v[62:65], v247, s[12:15], s7 offen nt
	s_mov_b32 s7, 0x28800
	buffer_load_dwordx4 v[66:69], v247, s[12:15], s7 offen nt
	s_mov_b32 s7, 0x2c800
	buffer_load_dwordx4 v[70:73], v247, s[12:15], s7 offen nt
	ds_write_b64 v249, v[74:75] offset:8640
	s_waitcnt lgkmcnt(0)
	ds_read_b128 v[74:77], v250 offset:4608
	ds_read_b128 v[78:81], v250 offset:4672
	s_waitcnt lgkmcnt(1)
	v_mfma_f32_16x16x32_bf16 v[74:77], v[74:77], v[2:5], 0
	ds_read_b128 v[82:85], v250 offset:6912
	s_waitcnt lgkmcnt(1)
	v_mfma_f32_16x16x32_bf16 v[74:77], v[78:81], v[6:9], v[74:77]
	ds_read_b128 v[78:81], v250 offset:6976
	s_waitcnt lgkmcnt(1)
	v_mfma_f32_16x16x32_bf16 v[82:85], v[82:85], v[2:5], 0
	s_waitcnt lgkmcnt(0)
	v_mfma_f32_16x16x32_bf16 v[78:81], v[78:81], v[6:9], v[82:85]
	s_nop 7
	v_cndmask_b32_e64 v209, v81, v77, s[2:3]
	v_cndmask_b32_e64 v208, v80, v76, s[2:3]
	v_cndmask_b32_e64 v211, v79, v75, s[2:3]
	v_cndmask_b32_e64 v210, v78, v74, s[2:3]
	s_waitcnt vmcnt(7)
	v_cvt_pk_bf16_f32 v42, v42, v43
	v_cvt_pk_bf16_f32 v43, v44, v45
	ds_write_b64 v249, v[42:43]
	s_waitcnt vmcnt(6)
	v_cvt_pk_bf16_f32 v42, v46, v47
	v_cvt_pk_bf16_f32 v43, v48, v49
	ds_write_b64 v249, v[42:43] offset:576
	s_waitcnt vmcnt(5)
	v_cvt_pk_bf16_f32 v42, v50, v51
	v_cvt_pk_bf16_f32 v43, v52, v53
	ds_write_b64 v249, v[42:43] offset:1152
	s_waitcnt vmcnt(4)
	v_cvt_pk_bf16_f32 v42, v54, v55
	v_cvt_pk_bf16_f32 v43, v56, v57
	ds_write_b64 v249, v[42:43] offset:1728
	s_waitcnt vmcnt(3)
	v_cvt_pk_bf16_f32 v42, v58, v59
	v_cvt_pk_bf16_f32 v43, v60, v61
	ds_write_b64 v249, v[42:43] offset:2304
	s_waitcnt vmcnt(2)
	v_cvt_pk_bf16_f32 v42, v62, v63
	v_cvt_pk_bf16_f32 v43, v64, v65
	ds_write_b64 v249, v[42:43] offset:2880
	s_waitcnt vmcnt(1)
	v_cvt_pk_bf16_f32 v42, v66, v67
	v_cvt_pk_bf16_f32 v43, v68, v69
	s_mov_b32 s7, 0x30800
	ds_write_b64 v249, v[42:43] offset:3456
	s_waitcnt vmcnt(0)
	v_cvt_pk_bf16_f32 v74, v70, v71
	v_cvt_pk_bf16_f32 v75, v72, v73
	buffer_load_dwordx4 v[42:45], v247, s[12:15], s55 offen nt
	buffer_load_dwordx4 v[46:49], v247, s[12:15], s56 offen nt
	buffer_load_dwordx4 v[50:53], v247, s[12:15], s57 offen nt
	buffer_load_dwordx4 v[54:57], v247, s[12:15], s62 offen nt
	buffer_load_dwordx4 v[58:61], v247, s[12:15], s7 offen nt
	s_mov_b32 s7, 0x34800
	buffer_load_dwordx4 v[62:65], v247, s[12:15], s7 offen nt
	s_mov_b32 s7, 0x38800
	buffer_load_dwordx4 v[66:69], v247, s[12:15], s7 offen nt
	s_mov_b32 s7, 0x3c800
	buffer_load_dwordx4 v[70:73], v247, s[12:15], s7 offen nt
	ds_write_b64 v249, v[74:75] offset:4032
	s_waitcnt lgkmcnt(0)
	ds_read_b128 v[74:77], v250
	ds_read_b128 v[78:81], v250 offset:64
	s_waitcnt lgkmcnt(1)
	v_mfma_f32_16x16x32_bf16 v[74:77], v[74:77], v[2:5], 0
	ds_read_b128 v[82:85], v250 offset:2304
	s_waitcnt lgkmcnt(1)
	v_mfma_f32_16x16x32_bf16 v[74:77], v[78:81], v[6:9], v[74:77]
	ds_read_b128 v[78:81], v250 offset:2368
	s_waitcnt lgkmcnt(1)
	v_mfma_f32_16x16x32_bf16 v[82:85], v[82:85], v[2:5], 0
	s_waitcnt lgkmcnt(0)
	v_mfma_f32_16x16x32_bf16 v[78:81], v[78:81], v[6:9], v[82:85]
	s_nop 7
	v_cndmask_b32_e64 v213, v81, v77, s[2:3]
	v_cndmask_b32_e64 v212, v80, v76, s[2:3]
	v_cndmask_b32_e64 v215, v79, v75, s[2:3]
	v_cndmask_b32_e64 v214, v78, v74, s[2:3]
	s_waitcnt vmcnt(7)
	v_cvt_pk_bf16_f32 v42, v42, v43
	v_cvt_pk_bf16_f32 v43, v44, v45
	ds_write_b64 v249, v[42:43] offset:4608
	s_waitcnt vmcnt(6)
	v_cvt_pk_bf16_f32 v42, v46, v47
	v_cvt_pk_bf16_f32 v43, v48, v49
	ds_write_b64 v249, v[42:43] offset:5184
	s_waitcnt vmcnt(5)
	v_cvt_pk_bf16_f32 v42, v50, v51
	v_cvt_pk_bf16_f32 v43, v52, v53
	ds_write_b64 v249, v[42:43] offset:5760
	s_waitcnt vmcnt(4)
	v_cvt_pk_bf16_f32 v42, v54, v55
	v_cvt_pk_bf16_f32 v43, v56, v57
	ds_write_b64 v249, v[42:43] offset:6336
	s_waitcnt vmcnt(3)
	v_cvt_pk_bf16_f32 v42, v58, v59
	v_cvt_pk_bf16_f32 v43, v60, v61
	ds_write_b64 v249, v[42:43] offset:6912
	s_waitcnt vmcnt(2)
	v_cvt_pk_bf16_f32 v42, v62, v63
	v_cvt_pk_bf16_f32 v43, v64, v65
	ds_write_b64 v249, v[42:43] offset:7488
	s_waitcnt vmcnt(1)
	v_cvt_pk_bf16_f32 v42, v66, v67
	v_cvt_pk_bf16_f32 v43, v68, v69
	s_mov_b32 s7, 0x40800
	ds_write_b64 v249, v[42:43] offset:8064
	s_waitcnt vmcnt(0)
	v_cvt_pk_bf16_f32 v74, v70, v71
	v_cvt_pk_bf16_f32 v75, v72, v73
	buffer_load_dwordx4 v[42:45], v247, s[12:15], s63 offen nt
	buffer_load_dwordx4 v[46:49], v247, s[12:15], s64 offen nt
	buffer_load_dwordx4 v[50:53], v247, s[12:15], s65 offen nt
	buffer_load_dwordx4 v[54:57], v247, s[12:15], s66 offen nt
	buffer_load_dwordx4 v[58:61], v247, s[12:15], s7 offen nt
	s_mov_b32 s7, 0x44800
	buffer_load_dwordx4 v[62:65], v247, s[12:15], s7 offen nt
	s_mov_b32 s7, 0x48800
	buffer_load_dwordx4 v[66:69], v247, s[12:15], s7 offen nt
	s_mov_b32 s7, 0x4c800
	buffer_load_dwordx4 v[70:73], v247, s[12:15], s7 offen nt
	ds_write_b64 v249, v[74:75] offset:8640
	s_waitcnt lgkmcnt(0)
	ds_read_b128 v[74:77], v250 offset:4608
	ds_read_b128 v[78:81], v250 offset:4672
	s_waitcnt lgkmcnt(1)
	v_mfma_f32_16x16x32_bf16 v[74:77], v[74:77], v[2:5], 0
	ds_read_b128 v[82:85], v250 offset:6912
	s_waitcnt lgkmcnt(1)
	v_mfma_f32_16x16x32_bf16 v[74:77], v[78:81], v[6:9], v[74:77]
	ds_read_b128 v[78:81], v250 offset:6976
	s_waitcnt lgkmcnt(1)
	v_mfma_f32_16x16x32_bf16 v[82:85], v[82:85], v[2:5], 0
	s_waitcnt lgkmcnt(0)
	v_mfma_f32_16x16x32_bf16 v[78:81], v[78:81], v[6:9], v[82:85]
	s_nop 7
	v_cndmask_b32_e64 v217, v81, v77, s[2:3]
	v_cndmask_b32_e64 v216, v80, v76, s[2:3]
	v_cndmask_b32_e64 v219, v79, v75, s[2:3]
	v_cndmask_b32_e64 v218, v78, v74, s[2:3]
	s_waitcnt vmcnt(7)
	v_cvt_pk_bf16_f32 v42, v42, v43
	v_cvt_pk_bf16_f32 v43, v44, v45
	ds_write_b64 v249, v[42:43]
	s_waitcnt vmcnt(6)
	v_cvt_pk_bf16_f32 v42, v46, v47
	v_cvt_pk_bf16_f32 v43, v48, v49
	ds_write_b64 v249, v[42:43] offset:576
	s_waitcnt vmcnt(5)
	v_cvt_pk_bf16_f32 v42, v50, v51
	v_cvt_pk_bf16_f32 v43, v52, v53
	ds_write_b64 v249, v[42:43] offset:1152
	s_waitcnt vmcnt(4)
	v_cvt_pk_bf16_f32 v42, v54, v55
	v_cvt_pk_bf16_f32 v43, v56, v57
	ds_write_b64 v249, v[42:43] offset:1728
	s_waitcnt vmcnt(3)
	v_cvt_pk_bf16_f32 v42, v58, v59
	v_cvt_pk_bf16_f32 v43, v60, v61
	ds_write_b64 v249, v[42:43] offset:2304
	s_waitcnt vmcnt(2)
	v_cvt_pk_bf16_f32 v42, v62, v63
	v_cvt_pk_bf16_f32 v43, v64, v65
	ds_write_b64 v249, v[42:43] offset:2880
	s_waitcnt vmcnt(1)
	v_cvt_pk_bf16_f32 v42, v66, v67
	v_cvt_pk_bf16_f32 v43, v68, v69
	s_mov_b32 s7, 0x50800
	ds_write_b64 v249, v[42:43] offset:3456
	s_waitcnt vmcnt(0)
	v_cvt_pk_bf16_f32 v74, v70, v71
	v_cvt_pk_bf16_f32 v75, v72, v73
	buffer_load_dwordx4 v[42:45], v247, s[12:15], s67 offen nt
	buffer_load_dwordx4 v[46:49], v247, s[12:15], s68 offen nt
	buffer_load_dwordx4 v[50:53], v247, s[12:15], s69 offen nt
	buffer_load_dwordx4 v[54:57], v247, s[12:15], s84 offen nt
	buffer_load_dwordx4 v[58:61], v247, s[12:15], s7 offen nt
	s_mov_b32 s7, 0x54800
	buffer_load_dwordx4 v[62:65], v247, s[12:15], s7 offen nt
	s_mov_b32 s7, 0x58800
	buffer_load_dwordx4 v[66:69], v247, s[12:15], s7 offen nt
	s_mov_b32 s7, 0x5c800
	buffer_load_dwordx4 v[70:73], v247, s[12:15], s7 offen nt
	ds_write_b64 v249, v[74:75] offset:4032
	s_waitcnt lgkmcnt(0)
	ds_read_b128 v[74:77], v250
	ds_read_b128 v[78:81], v250 offset:64
	s_waitcnt lgkmcnt(1)
	v_mfma_f32_16x16x32_bf16 v[74:77], v[74:77], v[2:5], 0
	ds_read_b128 v[82:85], v250 offset:2304
	s_waitcnt lgkmcnt(1)
	v_mfma_f32_16x16x32_bf16 v[74:77], v[78:81], v[6:9], v[74:77]
	ds_read_b128 v[78:81], v250 offset:2368
	s_waitcnt lgkmcnt(1)
	v_mfma_f32_16x16x32_bf16 v[82:85], v[82:85], v[2:5], 0
	s_waitcnt lgkmcnt(0)
	v_mfma_f32_16x16x32_bf16 v[78:81], v[78:81], v[6:9], v[82:85]
	s_nop 7
	v_cndmask_b32_e64 v221, v81, v77, s[2:3]
	v_cndmask_b32_e64 v220, v80, v76, s[2:3]
	v_cndmask_b32_e64 v223, v79, v75, s[2:3]
	v_cndmask_b32_e64 v222, v78, v74, s[2:3]
	s_waitcnt vmcnt(7)
	v_cvt_pk_bf16_f32 v42, v42, v43
	v_cvt_pk_bf16_f32 v43, v44, v45
	ds_write_b64 v249, v[42:43] offset:4608
	s_waitcnt vmcnt(6)
	v_cvt_pk_bf16_f32 v42, v46, v47
	v_cvt_pk_bf16_f32 v43, v48, v49
	ds_write_b64 v249, v[42:43] offset:5184
	s_waitcnt vmcnt(5)
	v_cvt_pk_bf16_f32 v42, v50, v51
	v_cvt_pk_bf16_f32 v43, v52, v53
	ds_write_b64 v249, v[42:43] offset:5760
	s_waitcnt vmcnt(4)
	v_cvt_pk_bf16_f32 v42, v54, v55
	v_cvt_pk_bf16_f32 v43, v56, v57
	ds_write_b64 v249, v[42:43] offset:6336
	s_waitcnt vmcnt(3)
	v_cvt_pk_bf16_f32 v42, v58, v59
	v_cvt_pk_bf16_f32 v43, v60, v61
	ds_write_b64 v249, v[42:43] offset:6912
	s_waitcnt vmcnt(2)
	v_cvt_pk_bf16_f32 v42, v62, v63
	v_cvt_pk_bf16_f32 v43, v64, v65
	ds_write_b64 v249, v[42:43] offset:7488
	s_waitcnt vmcnt(1)
	v_cvt_pk_bf16_f32 v42, v66, v67
	v_cvt_pk_bf16_f32 v43, v68, v69
	s_mov_b32 s7, 0x60800
	ds_write_b64 v249, v[42:43] offset:8064
	s_waitcnt vmcnt(0)
	v_cvt_pk_bf16_f32 v74, v70, v71
	v_cvt_pk_bf16_f32 v75, v72, v73
	buffer_load_dwordx4 v[42:45], v247, s[12:15], s85 offen nt
	buffer_load_dwordx4 v[46:49], v247, s[12:15], s86 offen nt
	buffer_load_dwordx4 v[50:53], v247, s[12:15], s87 offen nt
	buffer_load_dwordx4 v[54:57], v247, s[12:15], s92 offen nt
	buffer_load_dwordx4 v[58:61], v247, s[12:15], s7 offen nt
	s_mov_b32 s7, 0x64800
	buffer_load_dwordx4 v[62:65], v247, s[12:15], s7 offen nt
	s_mov_b32 s7, 0x68800
	buffer_load_dwordx4 v[66:69], v247, s[12:15], s7 offen nt
	s_mov_b32 s7, 0x6c800
	buffer_load_dwordx4 v[70:73], v247, s[12:15], s7 offen nt
	ds_write_b64 v249, v[74:75] offset:8640
	s_waitcnt lgkmcnt(0)
	ds_read_b128 v[74:77], v250 offset:4608
	ds_read_b128 v[78:81], v250 offset:4672
	s_waitcnt lgkmcnt(1)
	v_mfma_f32_16x16x32_bf16 v[74:77], v[74:77], v[2:5], 0
	ds_read_b128 v[82:85], v250 offset:6912
	s_waitcnt lgkmcnt(1)
	v_mfma_f32_16x16x32_bf16 v[74:77], v[78:81], v[6:9], v[74:77]
	ds_read_b128 v[78:81], v250 offset:6976
	s_waitcnt lgkmcnt(1)
	v_mfma_f32_16x16x32_bf16 v[82:85], v[82:85], v[2:5], 0
	s_waitcnt lgkmcnt(0)
	v_mfma_f32_16x16x32_bf16 v[78:81], v[78:81], v[6:9], v[82:85]
	s_nop 7
	v_cndmask_b32_e64 v225, v81, v77, s[2:3]
	v_cndmask_b32_e64 v224, v80, v76, s[2:3]
	v_cndmask_b32_e64 v227, v79, v75, s[2:3]
	v_cndmask_b32_e64 v226, v78, v74, s[2:3]
	s_waitcnt vmcnt(7)
	v_cvt_pk_bf16_f32 v42, v42, v43
	v_cvt_pk_bf16_f32 v43, v44, v45
	ds_write_b64 v249, v[42:43]
	s_waitcnt vmcnt(6)
	v_cvt_pk_bf16_f32 v42, v46, v47
	v_cvt_pk_bf16_f32 v43, v48, v49
	ds_write_b64 v249, v[42:43] offset:576
	s_waitcnt vmcnt(5)
	v_cvt_pk_bf16_f32 v42, v50, v51
	v_cvt_pk_bf16_f32 v43, v52, v53
	ds_write_b64 v249, v[42:43] offset:1152
	s_waitcnt vmcnt(4)
	v_cvt_pk_bf16_f32 v42, v54, v55
	v_cvt_pk_bf16_f32 v43, v56, v57
	ds_write_b64 v249, v[42:43] offset:1728
	s_waitcnt vmcnt(3)
	v_cvt_pk_bf16_f32 v42, v58, v59
	v_cvt_pk_bf16_f32 v43, v60, v61
	ds_write_b64 v249, v[42:43] offset:2304
	s_waitcnt vmcnt(2)
	v_cvt_pk_bf16_f32 v42, v62, v63
	v_cvt_pk_bf16_f32 v43, v64, v65
	ds_write_b64 v249, v[42:43] offset:2880
	s_waitcnt vmcnt(1)
	v_cvt_pk_bf16_f32 v42, v66, v67
	v_cvt_pk_bf16_f32 v43, v68, v69
	s_mov_b32 s7, 0x70800
	ds_write_b64 v249, v[42:43] offset:3456
	s_waitcnt vmcnt(0)
	v_cvt_pk_bf16_f32 v74, v70, v71
	v_cvt_pk_bf16_f32 v75, v72, v73
	buffer_load_dwordx4 v[42:45], v247, s[12:15], s94 offen nt
	buffer_load_dwordx4 v[46:49], v247, s[12:15], s95 offen nt
	buffer_load_dwordx4 v[50:53], v247, s[12:15], s96 offen nt
	buffer_load_dwordx4 v[54:57], v247, s[12:15], s97 offen nt
	buffer_load_dwordx4 v[58:61], v247, s[12:15], s7 offen nt
	s_mov_b32 s7, 0x74800
	buffer_load_dwordx4 v[62:65], v247, s[12:15], s7 offen nt
	s_mov_b32 s7, 0x78800
	buffer_load_dwordx4 v[66:69], v247, s[12:15], s7 offen nt
	s_mov_b32 s7, 0x7c800
	buffer_load_dwordx4 v[70:73], v247, s[12:15], s7 offen nt
	ds_write_b64 v249, v[74:75] offset:4032
	s_waitcnt lgkmcnt(0)
	ds_read_b128 v[74:77], v250
	ds_read_b128 v[78:81], v250 offset:64
	s_waitcnt lgkmcnt(1)
	v_mfma_f32_16x16x32_bf16 v[74:77], v[74:77], v[2:5], 0
	ds_read_b128 v[82:85], v250 offset:2304
	s_waitcnt lgkmcnt(1)
	v_mfma_f32_16x16x32_bf16 v[74:77], v[78:81], v[6:9], v[74:77]
	ds_read_b128 v[78:81], v250 offset:2368
	s_waitcnt lgkmcnt(1)
	v_mfma_f32_16x16x32_bf16 v[82:85], v[82:85], v[2:5], 0
	s_waitcnt lgkmcnt(0)
	v_mfma_f32_16x16x32_bf16 v[78:81], v[78:81], v[6:9], v[82:85]
	s_nop 7
	v_cndmask_b32_e64 v233, v81, v77, s[2:3]
	v_cndmask_b32_e64 v232, v80, v76, s[2:3]
	v_cndmask_b32_e64 v235, v79, v75, s[2:3]
	v_cndmask_b32_e64 v234, v78, v74, s[2:3]
	s_waitcnt vmcnt(7)
	v_cvt_pk_bf16_f32 v42, v42, v43
	v_cvt_pk_bf16_f32 v43, v44, v45
	ds_write_b64 v249, v[42:43] offset:4608
	s_waitcnt vmcnt(6)
	v_cvt_pk_bf16_f32 v42, v46, v47
	v_cvt_pk_bf16_f32 v43, v48, v49
	ds_write_b64 v249, v[42:43] offset:5184
	s_waitcnt vmcnt(5)
	v_cvt_pk_bf16_f32 v42, v50, v51
	v_cvt_pk_bf16_f32 v43, v52, v53
	ds_write_b64 v249, v[42:43] offset:5760
	s_waitcnt vmcnt(4)
	v_cvt_pk_bf16_f32 v42, v54, v55
	v_cvt_pk_bf16_f32 v43, v56, v57
	ds_write_b64 v249, v[42:43] offset:6336
	s_waitcnt vmcnt(3)
	v_cvt_pk_bf16_f32 v42, v58, v59
	v_cvt_pk_bf16_f32 v43, v60, v61
	ds_write_b64 v249, v[42:43] offset:6912
	s_waitcnt vmcnt(2)
	v_cvt_pk_bf16_f32 v42, v62, v63
	v_cvt_pk_bf16_f32 v43, v64, v65
	ds_write_b64 v249, v[42:43] offset:7488
	s_waitcnt vmcnt(1)
	v_cvt_pk_bf16_f32 v42, v66, v67
	v_cvt_pk_bf16_f32 v43, v68, v69
	ds_write_b64 v249, v[42:43] offset:8064
	s_waitcnt vmcnt(0)
	v_cvt_pk_bf16_f32 v42, v70, v71
	v_cvt_pk_bf16_f32 v43, v72, v73
	ds_write_b64 v249, v[42:43] offset:8640
	s_waitcnt lgkmcnt(0)
	ds_read_b128 v[42:45], v250 offset:4608
	ds_read_b128 v[46:49], v250 offset:4672
	s_waitcnt lgkmcnt(1)
	v_mfma_f32_16x16x32_bf16 v[42:45], v[42:45], v[2:5], 0
	ds_read_b128 v[50:53], v250 offset:6912
	s_waitcnt lgkmcnt(1)
	v_mfma_f32_16x16x32_bf16 v[42:45], v[46:49], v[6:9], v[42:45]
	ds_read_b128 v[46:49], v250 offset:6976
	s_waitcnt lgkmcnt(1)
	v_mfma_f32_16x16x32_bf16 v[50:53], v[50:53], v[2:5], 0
	s_waitcnt lgkmcnt(0)
	v_mfma_f32_16x16x32_bf16 v[46:49], v[46:49], v[6:9], v[50:53]
	s_nop 7
	v_cndmask_b32_e64 v231, v49, v45, s[2:3]
	v_cndmask_b32_e64 v230, v48, v44, s[2:3]
	v_cndmask_b32_e64 v229, v47, v43, s[2:3]
	v_cndmask_b32_e64 v228, v46, v42, s[2:3]
	s_and_b32 s17, s6, 0xffff
	s_mov_b32 s18, s14
	s_mov_b32 s19, s15
	s_movk_i32 s6, 0x2000
	buffer_load_dwordx4 v[98:101], v248, s[16:19], 0 offen nt
	buffer_load_dwordx4 v[94:97], v248, s[16:19], s6 offen nt
	buffer_load_dwordx4 v[90:93], v248, s[16:19], s43 offen nt
	buffer_load_dwordx4 v[86:89], v248, s[16:19], s46 offen nt
	s_mov_b32 s6, 0xa000
	buffer_load_dwordx4 v[82:85], v248, s[16:19], s6 offen nt
	s_mov_b32 s6, 0xe000
	buffer_load_dwordx4 v[74:77], v248, s[16:19], s6 offen nt
	buffer_load_dwordx4 v[78:81], v248, s[16:19], s47 offen nt
	buffer_load_dwordx4 v[70:73], v248, s[16:19], s48 offen nt
	s_mov_b32 s6, 0x12000
	buffer_load_dwordx4 v[66:69], v248, s[16:19], s6 offen nt
	s_mov_b32 s6, 0x16000
	buffer_load_dwordx4 v[58:61], v248, s[16:19], s6 offen nt
	buffer_load_dwordx4 v[62:65], v248, s[16:19], s49 offen nt
	buffer_load_dwordx4 v[54:57], v248, s[16:19], s50 offen nt
	s_movk_i32 s6, 0x6000
	buffer_load_dwordx4 v[102:105], v248, s[16:19], s6 offen nt
	buffer_load_dwordx4 v[46:49], v248, s[16:19], s51 offen nt
	s_mov_b32 s6, 0x1a000
	buffer_load_dwordx4 v[50:53], v248, s[16:19], s6 offen nt
	s_mov_b32 s6, 0x1e000
	buffer_load_dwordx4 v[42:45], v248, s[16:19], s6 offen nt
	s_cmp_eq_u32 s39, s5
	s_mov_b64 s[6:7], -1
	s_cbranch_scc1 .LBB0_723
	v_pk_add_f32 v[124:125], v[144:145], v[204:205]
	v_pk_add_f32 v[122:123], v[142:143], v[206:207]
	v_pk_add_f32 v[120:121], v[144:145], v[208:209]
	v_pk_add_f32 v[118:119], v[142:143], v[210:211]
	v_pk_add_f32 v[116:117], v[144:145], v[212:213]
	v_pk_add_f32 v[114:115], v[142:143], v[214:215]
	v_pk_add_f32 v[112:113], v[144:145], v[216:217]
	v_pk_add_f32 v[110:111], v[142:143], v[218:219]
	v_pk_add_f32 v[108:109], v[144:145], v[220:221]
	v_pk_add_f32 v[106:107], v[142:143], v[222:223]
	v_pk_add_f32 v[128:129], v[144:145], v[224:225]
	v_pk_add_f32 v[126:127], v[142:143], v[226:227]
	v_pk_add_f32 v[132:133], v[144:145], v[232:233]
	v_pk_add_f32 v[130:131], v[142:143], v[234:235]
	v_pk_add_f32 v[136:137], v[144:145], v[230:231]
	v_pk_add_f32 v[134:135], v[142:143], v[228:229]
	s_mov_b64 s[6:7], 0

.LBB0_725:
	v_max_f32_e32 v204, v125, v125
	v_max_f32_e32 v205, v124, v124
	v_max_f32_e32 v204, v205, v204
	v_max_f32_e32 v205, v121, v121
	v_max_f32_e32 v206, v120, v120
	v_max_f32_e32 v205, v206, v205
	v_max3_f32 v204, v122, v123, v204
	v_max3_f32 v205, v118, v119, v205
	s_mov_b32 s6, 0xf149f2ca
	v_max3_f32 v204, v204, s6, v205
	v_max_f32_e32 v205, v117, v117
	v_max_f32_e32 v206, v116, v116
	v_max_f32_e32 v205, v206, v205
	v_max_f32_e32 v206, v113, v113
	v_max_f32_e32 v207, v112, v112
	v_max_f32_e32 v206, v207, v206
	v_max3_f32 v205, v114, v115, v205
	v_max3_f32 v206, v110, v111, v206
	v_max3_f32 v204, v204, v205, v206
	v_max_f32_e32 v205, v109, v109
	v_max_f32_e32 v206, v108, v108
	v_max_f32_e32 v205, v206, v205
	v_max_f32_e32 v206, v129, v129
	v_max_f32_e32 v207, v128, v128
	v_max_f32_e32 v206, v207, v206
	v_max3_f32 v205, v106, v107, v205
	v_max3_f32 v206, v126, v127, v206
	v_max3_f32 v204, v204, v205, v206
	v_max_f32_e32 v205, v133, v133
	v_max_f32_e32 v206, v132, v132
	v_max_f32_e32 v205, v206, v205
	v_max_f32_e32 v206, v137, v137
	v_max_f32_e32 v207, v136, v136
	v_max_f32_e32 v206, v207, v206
	v_max3_f32 v205, v130, v131, v205
	v_max3_f32 v206, v134, v135, v206
	v_max3_f32 v204, v204, v205, v206
	v_and_b32_e32 v206, 64, v243
	v_xor_b32_e32 v205, 16, v243
	v_add_u32_e32 v207, 64, v206
	v_cmp_lt_i32_e32 vcc, v205, v207
	s_mov_b32 s18, s14
	s_mov_b32 s19, s15
	v_cndmask_b32_e32 v205, v243, v205, vcc
	v_lshlrev_b32_e32 v206, 2, v205
	ds_bpermute_b32 v205, v206, v204
	s_mov_b32 s6, 0x22000
	s_waitcnt lgkmcnt(0)
	v_max_f32_e32 v205, v205, v205
	v_max_f32_e32 v204, v204, v205
	v_xor_b32_e32 v205, 32, v243
	v_cmp_lt_i32_e32 vcc, v205, v207
	s_nop 1
	v_cndmask_b32_e32 v205, v243, v205, vcc
	v_lshlrev_b32_e32 v207, 2, v205
	ds_bpermute_b32 v205, v207, v204
	s_waitcnt lgkmcnt(0)
	v_max3_f32 v205, v236, v204, v205
	v_sub_f32_e32 v122, v122, v205
	v_exp_f32_e32 v221, v122
	v_sub_f32_e32 v123, v123, v205
	v_exp_f32_e32 v222, v123
	v_sub_f32_e32 v123, v124, v205
	v_exp_f32_e32 v223, v123
	v_sub_f32_e32 v123, v125, v205
	v_exp_f32_e32 v224, v123
	v_sub_f32_e32 v118, v118, v205
	v_add_f32_e32 v122, 0, v221
	v_exp_f32_e32 v225, v118
	v_sub_f32_e32 v119, v119, v205
	v_add_f32_e32 v122, v222, v122
	v_exp_f32_e32 v226, v119
	v_sub_f32_e32 v119, v120, v205
	v_add_f32_e32 v122, v223, v122
	v_exp_f32_e32 v227, v119
	v_sub_f32_e32 v119, v121, v205
	v_add_f32_e32 v122, v224, v122
	v_exp_f32_e32 v228, v119
	v_sub_f32_e32 v114, v114, v205
	v_add_f32_e32 v118, v225, v122
	v_exp_f32_e32 v213, v114
	v_sub_f32_e32 v115, v115, v205
	v_add_f32_e32 v118, v226, v118
	v_exp_f32_e32 v214, v115
	v_sub_f32_e32 v115, v116, v205
	v_add_f32_e32 v118, v227, v118
	v_exp_f32_e32 v215, v115
	v_sub_f32_e32 v115, v117, v205
	v_add_f32_e32 v118, v228, v118
	v_exp_f32_e32 v216, v115
	v_sub_f32_e32 v110, v110, v205
	v_add_f32_e32 v114, v213, v118
	v_exp_f32_e32 v217, v110
	v_sub_f32_e32 v111, v111, v205
	v_add_f32_e32 v114, v214, v114
	v_exp_f32_e32 v218, v111
	v_sub_f32_e32 v111, v112, v205
	v_add_f32_e32 v114, v215, v114
	v_exp_f32_e32 v219, v111
	v_sub_f32_e32 v111, v113, v205
	v_add_f32_e32 v114, v216, v114
	v_exp_f32_e32 v220, v111
	v_sub_f32_e32 v106, v106, v205
	v_add_f32_e32 v110, v217, v114
	v_exp_f32_e32 v208, v106
	v_sub_f32_e32 v107, v107, v205
	v_add_f32_e32 v110, v218, v110
	v_exp_f32_e32 v209, v107
	v_sub_f32_e32 v107, v108, v205
	v_add_f32_e32 v110, v219, v110
	v_exp_f32_e32 v210, v107
	v_sub_f32_e32 v107, v109, v205
	v_add_f32_e32 v110, v220, v110
	v_exp_f32_e32 v211, v107
	v_sub_f32_e32 v107, v126, v205
	v_add_f32_e32 v106, v208, v110
	v_exp_f32_e32 v212, v107
	v_sub_f32_e32 v107, v127, v205
	v_add_f32_e32 v106, v209, v106
	v_exp_f32_e32 v127, v107
	v_sub_f32_e32 v107, v128, v205
	v_add_f32_e32 v106, v210, v106
	v_exp_f32_e32 v128, v107
	v_sub_f32_e32 v107, v129, v205
	v_add_f32_e32 v106, v211, v106
	v_exp_f32_e32 v129, v107
	v_sub_f32_e32 v107, v130, v205
	v_add_f32_e32 v106, v212, v106
	v_exp_f32_e32 v119, v107
	v_sub_f32_e32 v107, v131, v205
	v_add_f32_e32 v106, v127, v106
	v_exp_f32_e32 v120, v107
	v_sub_f32_e32 v107, v132, v205
	v_add_f32_e32 v106, v128, v106
	v_exp_f32_e32 v121, v107
	v_sub_f32_e32 v107, v133, v205
	v_add_f32_e32 v106, v129, v106
	v_exp_f32_e32 v122, v107
	v_add_f32_e32 v106, v119, v106
	v_add_f32_e32 v106, v120, v106
	v_add_f32_e32 v106, v121, v106
	v_sub_f32_e32 v204, v236, v205
	v_add_f32_e32 v118, v122, v106
	v_sub_f32_e32 v106, v134, v205
	v_exp_f32_e32 v204, v204
	v_exp_f32_e32 v123, v106
	v_sub_f32_e32 v106, v135, v205
	v_exp_f32_e32 v124, v106
	v_sub_f32_e32 v106, v136, v205
	v_exp_f32_e32 v125, v106
	v_sub_f32_e32 v106, v137, v205
	v_exp_f32_e32 v126, v106
	v_pk_mul_f32 v[110:111], v[22:23], v[204:205] op_sel_hi:[1,0]
	v_pk_mul_f32 v[22:23], v[18:19], v[204:205] op_sel_hi:[1,0]
	v_pk_mul_f32 v[18:19], v[30:31], v[204:205] op_sel_hi:[1,0]
	v_add_f32_e32 v30, v123, v118
	v_add_f32_e32 v30, v124, v30
	v_add_f32_e32 v30, v125, v30
	v_add_f32_e32 v118, v126, v30
	s_waitcnt vmcnt(15)
	v_cvt_pk_bf16_f32 v30, v98, v99
	v_cvt_pk_bf16_f32 v31, v100, v101
	ds_write_b64 v251, v[30:31]
	s_waitcnt vmcnt(14)
	v_cvt_pk_bf16_f32 v30, v94, v95
	v_cvt_pk_bf16_f32 v31, v96, v97
	ds_write_b64 v251, v[30:31] offset:576
	s_waitcnt vmcnt(13)
	v_cvt_pk_bf16_f32 v30, v90, v91
	v_cvt_pk_bf16_f32 v31, v92, v93
	ds_write_b64 v251, v[30:31] offset:1152
	s_waitcnt vmcnt(3)
	v_cvt_pk_bf16_f32 v30, v102, v103
	v_cvt_pk_bf16_f32 v31, v104, v105
	ds_write_b64 v251, v[30:31] offset:1728
	v_cvt_pk_bf16_f32 v30, v86, v87
	v_cvt_pk_bf16_f32 v31, v88, v89
	ds_write_b64 v251, v[30:31] offset:2304
	v_cvt_pk_bf16_f32 v30, v82, v83
	v_cvt_pk_bf16_f32 v31, v84, v85
	ds_write_b64 v251, v[30:31] offset:2880
	v_cvt_pk_bf16_f32 v30, v78, v79
	v_cvt_pk_bf16_f32 v31, v80, v81
	ds_write_b64 v251, v[30:31] offset:3456
	v_cvt_pk_bf16_f32 v30, v74, v75
	v_cvt_pk_bf16_f32 v31, v76, v77
	ds_write_b64 v251, v[30:31] offset:4032
	v_cvt_pk_bf16_f32 v30, v70, v71
	v_cvt_pk_bf16_f32 v31, v72, v73
	ds_write_b64 v251, v[30:31] offset:4608
	v_cvt_pk_bf16_f32 v30, v66, v67
	v_cvt_pk_bf16_f32 v31, v68, v69
	ds_write_b64 v251, v[30:31] offset:5184
	v_cvt_pk_bf16_f32 v30, v62, v63
	v_cvt_pk_bf16_f32 v31, v64, v65
	ds_write_b64 v251, v[30:31] offset:5760
	v_cvt_pk_bf16_f32 v30, v58, v59
	v_cvt_pk_bf16_f32 v31, v60, v61
	ds_write_b64 v251, v[30:31] offset:6336
	v_cvt_pk_bf16_f32 v30, v54, v55
	v_cvt_pk_bf16_f32 v31, v56, v57
	ds_write_b64 v251, v[30:31] offset:6912
	s_waitcnt vmcnt(1)
	v_cvt_pk_bf16_f32 v30, v50, v51
	v_cvt_pk_bf16_f32 v31, v52, v53
	ds_write_b64 v251, v[30:31] offset:7488
	v_cvt_pk_bf16_f32 v30, v46, v47
	v_cvt_pk_bf16_f32 v31, v48, v49
	ds_write_b64 v251, v[30:31] offset:8064
	s_waitcnt vmcnt(0)
	v_cvt_pk_bf16_f32 v30, v42, v43
	v_cvt_pk_bf16_f32 v31, v44, v45
	ds_write_b64 v251, v[30:31] offset:8640
	buffer_load_dwordx4 v[90:93], v248, s[16:19], s15 offen nt
	buffer_load_dwordx4 v[86:89], v248, s[16:19], s6 offen nt
	buffer_load_dwordx4 v[82:85], v248, s[16:19], s52 offen nt
	s_mov_b32 s6, 0x26000
	buffer_load_dwordx4 v[78:81], v248, s[16:19], s6 offen nt
	buffer_load_dwordx4 v[74:77], v248, s[16:19], s53 offen nt
	s_mov_b32 s6, 0x2a000
	buffer_load_dwordx4 v[70:73], v248, s[16:19], s6 offen nt
	buffer_load_dwordx4 v[66:69], v248, s[16:19], s54 offen nt
	s_mov_b32 s6, 0x2e000
	buffer_load_dwordx4 v[62:65], v248, s[16:19], s6 offen nt
	buffer_load_dwordx4 v[58:61], v248, s[16:19], s55 offen nt
	s_mov_b32 s6, 0x32000
	buffer_load_dwordx4 v[54:57], v248, s[16:19], s6 offen nt
	buffer_load_dwordx4 v[50:53], v248, s[16:19], s56 offen nt
	s_mov_b32 s6, 0x36000
	buffer_load_dwordx4 v[46:49], v248, s[16:19], s6 offen nt
	buffer_load_dwordx4 v[42:45], v248, s[16:19], s57 offen nt
	s_mov_b32 s6, 0x3a000
	v_pk_mul_f32 v[116:117], v[28:29], v[204:205] op_sel_hi:[1,0]
	v_pk_mul_f32 v[114:115], v[26:27], v[204:205] op_sel_hi:[1,0]
	v_pk_mul_f32 v[108:109], v[16:17], v[204:205] op_sel_hi:[1,0]
	v_pk_mul_f32 v[106:107], v[14:15], v[204:205] op_sel_hi:[1,0]
	v_pk_mul_f32 v[28:29], v[12:13], v[204:205] op_sel_hi:[1,0]
	v_pk_mul_f32 v[26:27], v[10:11], v[204:205] op_sel_hi:[1,0]
	v_pk_mul_f32 v[16:17], v[36:37], v[204:205] op_sel_hi:[1,0]
	v_pk_mul_f32 v[14:15], v[34:35], v[204:205] op_sel_hi:[1,0]
	v_pk_mul_f32 v[12:13], v[40:41], v[204:205] op_sel_hi:[1,0]
	v_pk_mul_f32 v[10:11], v[38:39], v[204:205] op_sel_hi:[1,0]
	buffer_load_dwordx4 v[38:41], v248, s[16:19], s6 offen nt
	buffer_load_dwordx4 v[34:37], v248, s[16:19], s62 offen nt
	s_mov_b32 s6, 0x3e000
	v_pk_mul_f32 v[112:113], v[24:25], v[204:205] op_sel_hi:[1,0]
	v_pk_mul_f32 v[24:25], v[20:21], v[204:205] op_sel_hi:[1,0]
	v_pk_mul_f32 v[20:21], v[32:33], v[204:205] op_sel_hi:[1,0]
	buffer_load_dwordx4 v[30:33], v248, s[16:19], s6 offen nt
	s_waitcnt lgkmcnt(0)
	v_cvt_pk_bf16_f32 v130, v221, v222
	v_cvt_pk_bf16_f32 v131, v223, v224
	v_cvt_pk_bf16_f32 v132, v225, v226
	v_cvt_pk_bf16_f32 v133, v227, v228
	ds_read_b64_tr_b16 v[96:97], v252 offset:4608
	ds_read_b64_tr_b16 v[94:95], v252
	ds_read_b64_tr_b16 v[98:99], v252 offset:32
	ds_read_b64_tr_b16 v[100:101], v252 offset:4640
	ds_read_b64_tr_b16 v[102:103], v252 offset:64
	ds_read_b64_tr_b16 v[104:105], v252 offset:4672
	s_waitcnt lgkmcnt(0)
	v_mfma_f32_16x16x32_bf16 v[102:105], v[102:105], v[130:133], v[106:109]
	s_nop 2
	ds_read_b64_tr_b16 v[106:107], v252 offset:96
	ds_read_b64_tr_b16 v[108:109], v252 offset:4704
	s_waitcnt lgkmcnt(0)
	v_mfma_f32_16x16x32_bf16 v[26:29], v[106:109], v[130:133], v[26:29]
	v_mfma_f32_16x16x32_bf16 v[94:97], v[94:97], v[130:133], v[114:117]
	v_mfma_f32_16x16x32_bf16 v[98:101], v[98:101], v[130:133], v[110:113]
	ds_read_b64_tr_b16 v[108:109], v252 offset:4736
	ds_read_b64_tr_b16 v[106:107], v252 offset:128
	s_nop 0
	ds_read_b64_tr_b16 v[110:111], v252 offset:160
	ds_read_b64_tr_b16 v[112:113], v252 offset:4768
	s_waitcnt lgkmcnt(2)
	v_mfma_f32_16x16x32_bf16 v[22:25], v[106:109], v[130:133], v[22:25]
	ds_read_b64_tr_b16 v[106:107], v252 offset:192
	ds_read_b64_tr_b16 v[108:109], v252 offset:4800
	s_waitcnt lgkmcnt(0)
	v_mfma_f32_16x16x32_bf16 v[14:17], v[106:109], v[130:133], v[14:17]
	ds_read_b64_tr_b16 v[106:107], v252 offset:224
	ds_read_b64_tr_b16 v[108:109], v252 offset:4832
	v_mfma_f32_16x16x32_bf16 v[18:21], v[110:113], v[130:133], v[18:21]
	s_waitcnt lgkmcnt(0)
	v_mfma_f32_16x16x32_bf16 v[10:13], v[106:109], v[130:133], v[10:13]
	s_waitcnt lgkmcnt(0)
	s_waitcnt vmcnt(15)
	v_cvt_pk_bf16_f32 v90, v90, v91
	v_cvt_pk_bf16_f32 v91, v92, v93
	ds_write_b64 v251, v[90:91]
	s_waitcnt vmcnt(14)
	v_cvt_pk_bf16_f32 v86, v86, v87
	v_cvt_pk_bf16_f32 v87, v88, v89
	ds_write_b64 v251, v[86:87] offset:576
	s_waitcnt vmcnt(13)
	v_cvt_pk_bf16_f32 v82, v82, v83
	v_cvt_pk_bf16_f32 v83, v84, v85
	ds_write_b64 v251, v[82:83] offset:1152
	s_waitcnt vmcnt(12)
	v_cvt_pk_bf16_f32 v78, v78, v79
	v_cvt_pk_bf16_f32 v79, v80, v81
	ds_write_b64 v251, v[78:79] offset:1728
	s_waitcnt vmcnt(11)
	v_cvt_pk_bf16_f32 v74, v74, v75
	v_cvt_pk_bf16_f32 v75, v76, v77
	ds_write_b64 v251, v[74:75] offset:2304
	s_waitcnt vmcnt(10)
	v_cvt_pk_bf16_f32 v70, v70, v71
	v_cvt_pk_bf16_f32 v71, v72, v73
	ds_write_b64 v251, v[70:71] offset:2880
	s_waitcnt vmcnt(9)
	v_cvt_pk_bf16_f32 v66, v66, v67
	v_cvt_pk_bf16_f32 v67, v68, v69
	ds_write_b64 v251, v[66:67] offset:3456
	s_waitcnt vmcnt(8)
	v_cvt_pk_bf16_f32 v62, v62, v63
	v_cvt_pk_bf16_f32 v63, v64, v65
	ds_write_b64 v251, v[62:63] offset:4032
	s_waitcnt vmcnt(7)
	v_cvt_pk_bf16_f32 v58, v58, v59
	v_cvt_pk_bf16_f32 v59, v60, v61
	ds_write_b64 v251, v[58:59] offset:4608
	s_waitcnt vmcnt(6)
	v_cvt_pk_bf16_f32 v54, v54, v55
	v_cvt_pk_bf16_f32 v55, v56, v57
	ds_write_b64 v251, v[54:55] offset:5184
	s_waitcnt vmcnt(5)
	v_cvt_pk_bf16_f32 v50, v50, v51
	v_cvt_pk_bf16_f32 v51, v52, v53
	ds_write_b64 v251, v[50:51] offset:5760
	s_waitcnt vmcnt(4)
	v_cvt_pk_bf16_f32 v46, v46, v47
	v_cvt_pk_bf16_f32 v47, v48, v49
	ds_write_b64 v251, v[46:47] offset:6336
	s_waitcnt vmcnt(3)
	v_cvt_pk_bf16_f32 v42, v42, v43
	v_cvt_pk_bf16_f32 v43, v44, v45
	ds_write_b64 v251, v[42:43] offset:6912
	s_waitcnt vmcnt(2)
	v_cvt_pk_bf16_f32 v38, v38, v39
	v_cvt_pk_bf16_f32 v39, v40, v41
	ds_write_b64 v251, v[38:39] offset:7488
	s_waitcnt vmcnt(1)
	v_cvt_pk_bf16_f32 v34, v34, v35
	v_cvt_pk_bf16_f32 v35, v36, v37
	ds_write_b64 v251, v[34:35] offset:8064
	s_waitcnt vmcnt(0)
	v_cvt_pk_bf16_f32 v30, v30, v31
	v_cvt_pk_bf16_f32 v31, v32, v33
	ds_write_b64 v251, v[30:31] offset:8640
	s_mov_b32 s6, 0x42000
	buffer_load_dwordx4 v[70:73], v248, s[16:19], s63 offen nt
	buffer_load_dwordx4 v[74:77], v248, s[16:19], s6 offen nt
	buffer_load_dwordx4 v[78:81], v248, s[16:19], s64 offen nt
	s_mov_b32 s6, 0x46000
	buffer_load_dwordx4 v[82:85], v248, s[16:19], s6 offen nt
	buffer_load_dwordx4 v[86:89], v248, s[16:19], s65 offen nt
	s_mov_b32 s6, 0x4a000
	buffer_load_dwordx4 v[90:93], v248, s[16:19], s6 offen nt
	buffer_load_dwordx4 v[106:109], v248, s[16:19], s66 offen nt
	s_mov_b32 s6, 0x4e000
	buffer_load_dwordx4 v[110:113], v248, s[16:19], s6 offen nt
	buffer_load_dwordx4 v[114:117], v248, s[16:19], s67 offen nt
	s_mov_b32 s6, 0x52000
	buffer_load_dwordx4 v[66:69], v248, s[16:19], s6 offen nt
	buffer_load_dwordx4 v[62:65], v248, s[16:19], s68 offen nt
	s_mov_b32 s6, 0x56000
	buffer_load_dwordx4 v[58:61], v248, s[16:19], s6 offen nt
	buffer_load_dwordx4 v[54:57], v248, s[16:19], s69 offen nt
	s_mov_b32 s6, 0x5a000
	buffer_load_dwordx4 v[50:53], v248, s[16:19], s6 offen nt
	buffer_load_dwordx4 v[46:49], v248, s[16:19], s84 offen nt
	s_mov_b32 s6, 0x5e000
	buffer_load_dwordx4 v[42:45], v248, s[16:19], s6 offen nt
	s_waitcnt lgkmcnt(0)
	v_cvt_pk_bf16_f32 v130, v213, v214
	v_cvt_pk_bf16_f32 v131, v215, v216
	v_cvt_pk_bf16_f32 v132, v217, v218
	v_cvt_pk_bf16_f32 v133, v219, v220
	ds_read_b64_tr_b16 v[32:33], v252 offset:4608
	ds_read_b64_tr_b16 v[30:31], v252
	ds_read_b64_tr_b16 v[34:35], v252 offset:32
	ds_read_b64_tr_b16 v[36:37], v252 offset:4640
	s_waitcnt lgkmcnt(2)
	v_mfma_f32_16x16x32_bf16 v[30:33], v[30:33], v[130:133], v[94:97]
	ds_read_b64_tr_b16 v[38:39], v252 offset:64
	ds_read_b64_tr_b16 v[40:41], v252 offset:4672
	s_nop 0
	ds_read_b64_tr_b16 v[94:95], v252 offset:96
	ds_read_b64_tr_b16 v[96:97], v252 offset:4704
	s_waitcnt lgkmcnt(4)
	v_mfma_f32_16x16x32_bf16 v[34:37], v[34:37], v[130:133], v[98:101]
	s_waitcnt lgkmcnt(2)
	v_mfma_f32_16x16x32_bf16 v[38:41], v[38:41], v[130:133], v[102:105]
	s_waitcnt lgkmcnt(0)
	v_mfma_f32_16x16x32_bf16 v[26:29], v[94:97], v[130:133], v[26:29]
	ds_read_b64_tr_b16 v[96:97], v252 offset:4736
	ds_read_b64_tr_b16 v[94:95], v252 offset:128
	ds_read_b64_tr_b16 v[98:99], v252 offset:160
	ds_read_b64_tr_b16 v[100:101], v252 offset:4768
	s_waitcnt lgkmcnt(2)
	v_mfma_f32_16x16x32_bf16 v[22:25], v[94:97], v[130:133], v[22:25]
	ds_read_b64_tr_b16 v[94:95], v252 offset:192
	ds_read_b64_tr_b16 v[96:97], v252 offset:4800
	s_waitcnt lgkmcnt(0)
	v_mfma_f32_16x16x32_bf16 v[14:17], v[94:97], v[130:133], v[14:17]
	ds_read_b64_tr_b16 v[94:95], v252 offset:224
	ds_read_b64_tr_b16 v[96:97], v252 offset:4832
	v_mfma_f32_16x16x32_bf16 v[18:21], v[98:101], v[130:133], v[18:21]
	s_waitcnt lgkmcnt(0)
	v_mfma_f32_16x16x32_bf16 v[10:13], v[94:97], v[130:133], v[10:13]
	s_waitcnt lgkmcnt(0)
	s_waitcnt vmcnt(15)
	v_cvt_pk_bf16_f32 v70, v70, v71
	v_cvt_pk_bf16_f32 v71, v72, v73
	ds_write_b64 v251, v[70:71]
	s_waitcnt vmcnt(14)
	v_cvt_pk_bf16_f32 v70, v74, v75
	v_cvt_pk_bf16_f32 v71, v76, v77
	ds_write_b64 v251, v[70:71] offset:576
	s_waitcnt vmcnt(13)
	v_cvt_pk_bf16_f32 v70, v78, v79
	v_cvt_pk_bf16_f32 v71, v80, v81
	ds_write_b64 v251, v[70:71] offset:1152
	s_waitcnt vmcnt(12)
	v_cvt_pk_bf16_f32 v70, v82, v83
	v_cvt_pk_bf16_f32 v71, v84, v85
	ds_write_b64 v251, v[70:71] offset:1728
	s_waitcnt vmcnt(11)
	v_cvt_pk_bf16_f32 v70, v86, v87
	v_cvt_pk_bf16_f32 v71, v88, v89
	ds_write_b64 v251, v[70:71] offset:2304
	s_waitcnt vmcnt(10)
	v_cvt_pk_bf16_f32 v70, v90, v91
	v_cvt_pk_bf16_f32 v71, v92, v93
	ds_write_b64 v251, v[70:71] offset:2880
	s_waitcnt vmcnt(9)
	v_cvt_pk_bf16_f32 v70, v106, v107
	v_cvt_pk_bf16_f32 v71, v108, v109
	ds_write_b64 v251, v[70:71] offset:3456
	s_waitcnt vmcnt(8)
	v_cvt_pk_bf16_f32 v70, v110, v111
	v_cvt_pk_bf16_f32 v71, v112, v113
	ds_write_b64 v251, v[70:71] offset:4032
	s_waitcnt vmcnt(7)
	v_cvt_pk_bf16_f32 v70, v114, v115
	v_cvt_pk_bf16_f32 v71, v116, v117
	ds_write_b64 v251, v[70:71] offset:4608
	s_waitcnt vmcnt(6)
	v_cvt_pk_bf16_f32 v66, v66, v67
	v_cvt_pk_bf16_f32 v67, v68, v69
	ds_write_b64 v251, v[66:67] offset:5184
	s_waitcnt vmcnt(5)
	v_cvt_pk_bf16_f32 v62, v62, v63
	v_cvt_pk_bf16_f32 v63, v64, v65
	ds_write_b64 v251, v[62:63] offset:5760
	s_waitcnt vmcnt(4)
	v_cvt_pk_bf16_f32 v58, v58, v59
	v_cvt_pk_bf16_f32 v59, v60, v61
	ds_write_b64 v251, v[58:59] offset:6336
	s_waitcnt vmcnt(3)
	v_cvt_pk_bf16_f32 v54, v54, v55
	v_cvt_pk_bf16_f32 v55, v56, v57
	ds_write_b64 v251, v[54:55] offset:6912
	s_waitcnt vmcnt(2)
	v_cvt_pk_bf16_f32 v50, v50, v51
	v_cvt_pk_bf16_f32 v51, v52, v53
	ds_write_b64 v251, v[50:51] offset:7488
	s_waitcnt vmcnt(1)
	v_cvt_pk_bf16_f32 v46, v46, v47
	v_cvt_pk_bf16_f32 v47, v48, v49
	ds_write_b64 v251, v[46:47] offset:8064
	s_waitcnt vmcnt(0)
	v_cvt_pk_bf16_f32 v42, v42, v43
	v_cvt_pk_bf16_f32 v43, v44, v45
	ds_write_b64 v251, v[42:43] offset:8640
	s_mov_b32 s6, 0x62000
	buffer_load_dwordx4 v[90:93], v248, s[16:19], s85 offen nt
	buffer_load_dwordx4 v[94:97], v248, s[16:19], s6 offen nt
	buffer_load_dwordx4 v[98:101], v248, s[16:19], s86 offen nt
	s_mov_b32 s6, 0x66000
	buffer_load_dwordx4 v[102:105], v248, s[16:19], s6 offen nt
	buffer_load_dwordx4 v[106:109], v248, s[16:19], s87 offen nt
	s_mov_b32 s6, 0x6a000
	buffer_load_dwordx4 v[110:113], v248, s[16:19], s6 offen nt
	buffer_load_dwordx4 v[114:117], v248, s[16:19], s92 offen nt
	s_mov_b32 s6, 0x6e000
	buffer_load_dwordx4 v[130:133], v248, s[16:19], s6 offen nt
	buffer_load_dwordx4 v[134:137], v248, s[16:19], s94 offen nt
	s_mov_b32 s6, 0x72000
	buffer_load_dwordx4 v[86:89], v248, s[16:19], s6 offen nt
	buffer_load_dwordx4 v[82:85], v248, s[16:19], s95 offen nt
	s_mov_b32 s6, 0x76000
	buffer_load_dwordx4 v[78:81], v248, s[16:19], s6 offen nt
	buffer_load_dwordx4 v[54:57], v248, s[16:19], s96 offen nt
	s_mov_b32 s6, 0x7a000
	buffer_load_dwordx4 v[50:53], v248, s[16:19], s6 offen nt
	buffer_load_dwordx4 v[46:49], v248, s[16:19], s97 offen nt
	s_mov_b32 s6, 0x7e000
	buffer_load_dwordx4 v[42:45], v248, s[16:19], s6 offen nt
	s_waitcnt lgkmcnt(0)
	v_cvt_pk_bf16_f32 v74, v208, v209
	v_cvt_pk_bf16_f32 v75, v210, v211
	v_cvt_pk_bf16_f32 v76, v212, v127
	v_cvt_pk_bf16_f32 v77, v128, v129
	ds_read_b64_tr_b16 v[60:61], v252 offset:4608
	ds_read_b64_tr_b16 v[58:59], v252
	ds_read_b64_tr_b16 v[62:63], v252 offset:32
	ds_read_b64_tr_b16 v[64:65], v252 offset:4640
	s_waitcnt lgkmcnt(2)
	v_mfma_f32_16x16x32_bf16 v[30:33], v[58:61], v[74:77], v[30:33]
	ds_read_b64_tr_b16 v[58:59], v252 offset:64
	ds_read_b64_tr_b16 v[60:61], v252 offset:4672
	s_waitcnt lgkmcnt(0)
	v_mfma_f32_16x16x32_bf16 v[38:41], v[58:61], v[74:77], v[38:41]
	ds_read_b64_tr_b16 v[58:59], v252 offset:96
	ds_read_b64_tr_b16 v[60:61], v252 offset:4704
	v_mfma_f32_16x16x32_bf16 v[34:37], v[62:65], v[74:77], v[34:37]
	s_waitcnt lgkmcnt(0)
	v_mfma_f32_16x16x32_bf16 v[58:61], v[58:61], v[74:77], v[26:29]
	s_nop 2
	ds_read_b64_tr_b16 v[28:29], v252 offset:4736
	ds_read_b64_tr_b16 v[26:27], v252 offset:128
	ds_read_b64_tr_b16 v[66:67], v252 offset:160
	ds_read_b64_tr_b16 v[68:69], v252 offset:4768
	s_waitcnt lgkmcnt(2)
	v_mfma_f32_16x16x32_bf16 v[62:65], v[26:29], v[74:77], v[22:25]
	s_waitcnt lgkmcnt(0)
	v_mfma_f32_16x16x32_bf16 v[66:69], v[66:69], v[74:77], v[18:21]
	s_nop 2
	ds_read_b64_tr_b16 v[18:19], v252 offset:192
	ds_read_b64_tr_b16 v[20:21], v252 offset:4800
	s_waitcnt lgkmcnt(0)
	v_mfma_f32_16x16x32_bf16 v[70:73], v[18:21], v[74:77], v[14:17]
	s_nop 2
	ds_read_b64_tr_b16 v[14:15], v252 offset:224
	ds_read_b64_tr_b16 v[16:17], v252 offset:4832
	s_waitcnt lgkmcnt(0)
	v_mfma_f32_16x16x32_bf16 v[74:77], v[14:17], v[74:77], v[10:13]
	s_waitcnt lgkmcnt(0)
	s_waitcnt vmcnt(15)
	v_cvt_pk_bf16_f32 v10, v90, v91
	v_cvt_pk_bf16_f32 v11, v92, v93
	ds_write_b64 v251, v[10:11]
	s_waitcnt vmcnt(14)
	v_cvt_pk_bf16_f32 v10, v94, v95
	v_cvt_pk_bf16_f32 v11, v96, v97
	ds_write_b64 v251, v[10:11] offset:576
	s_waitcnt vmcnt(13)
	v_cvt_pk_bf16_f32 v10, v98, v99
	v_cvt_pk_bf16_f32 v11, v100, v101
	ds_write_b64 v251, v[10:11] offset:1152
	s_waitcnt vmcnt(12)
	v_cvt_pk_bf16_f32 v10, v102, v103
	v_cvt_pk_bf16_f32 v11, v104, v105
	ds_write_b64 v251, v[10:11] offset:1728
	s_waitcnt vmcnt(11)
	v_cvt_pk_bf16_f32 v10, v106, v107
	v_cvt_pk_bf16_f32 v11, v108, v109
	ds_write_b64 v251, v[10:11] offset:2304
	s_waitcnt vmcnt(10)
	v_cvt_pk_bf16_f32 v10, v110, v111
	v_cvt_pk_bf16_f32 v11, v112, v113
	ds_write_b64 v251, v[10:11] offset:2880
	s_waitcnt vmcnt(9)
	v_cvt_pk_bf16_f32 v10, v114, v115
	v_cvt_pk_bf16_f32 v11, v116, v117
	ds_write_b64 v251, v[10:11] offset:3456
	s_waitcnt vmcnt(8)
	v_cvt_pk_bf16_f32 v10, v130, v131
	v_cvt_pk_bf16_f32 v11, v132, v133
	ds_write_b64 v251, v[10:11] offset:4032
	s_waitcnt vmcnt(7)
	v_cvt_pk_bf16_f32 v10, v134, v135
	v_cvt_pk_bf16_f32 v11, v136, v137
	ds_write_b64 v251, v[10:11] offset:4608
	s_waitcnt vmcnt(6)
	v_cvt_pk_bf16_f32 v10, v86, v87
	v_cvt_pk_bf16_f32 v11, v88, v89
	ds_write_b64 v251, v[10:11] offset:5184
	s_waitcnt vmcnt(5)
	v_cvt_pk_bf16_f32 v10, v82, v83
	v_cvt_pk_bf16_f32 v11, v84, v85
	ds_write_b64 v251, v[10:11] offset:5760
	s_waitcnt vmcnt(4)
	v_cvt_pk_bf16_f32 v10, v78, v79
	v_cvt_pk_bf16_f32 v11, v80, v81
	ds_write_b64 v251, v[10:11] offset:6336
	s_waitcnt vmcnt(3)
	v_cvt_pk_bf16_f32 v10, v54, v55
	v_cvt_pk_bf16_f32 v11, v56, v57
	ds_write_b64 v251, v[10:11] offset:6912
	s_waitcnt vmcnt(2)
	v_cvt_pk_bf16_f32 v10, v50, v51
	v_cvt_pk_bf16_f32 v11, v52, v53
	ds_write_b64 v251, v[10:11] offset:7488
	s_waitcnt vmcnt(1)
	v_cvt_pk_bf16_f32 v10, v46, v47
	v_cvt_pk_bf16_f32 v11, v48, v49
	ds_write_b64 v251, v[10:11] offset:8064
	s_waitcnt vmcnt(0)
	v_cvt_pk_bf16_f32 v10, v42, v43
	v_cvt_pk_bf16_f32 v11, v44, v45
	ds_write_b64 v251, v[10:11] offset:8640
	s_waitcnt lgkmcnt(0)
	v_cvt_pk_bf16_f32 v42, v119, v120
	v_cvt_pk_bf16_f32 v43, v121, v122
	v_cvt_pk_bf16_f32 v44, v123, v124
	v_cvt_pk_bf16_f32 v45, v125, v126
	ds_read_b64_tr_b16 v[10:11], v252
	ds_read_b64_tr_b16 v[12:13], v252 offset:4608
	ds_read_b64_tr_b16 v[16:17], v252 offset:4640
	ds_read_b64_tr_b16 v[14:15], v252 offset:32
	ds_read_b64_tr_b16 v[18:19], v252 offset:64
	ds_read_b64_tr_b16 v[46:47], v252 offset:96
	ds_read_b64_tr_b16 v[20:21], v252 offset:4672
	ds_read_b64_tr_b16 v[48:49], v252 offset:4704
	s_waitcnt lgkmcnt(6)
	v_mfma_f32_16x16x32_bf16 v[26:29], v[10:13], v[42:45], v[30:33]
	s_waitcnt lgkmcnt(4)
	v_mfma_f32_16x16x32_bf16 v[22:25], v[14:17], v[42:45], v[34:37]
	s_waitcnt lgkmcnt(1)
	v_mfma_f32_16x16x32_bf16 v[14:17], v[18:21], v[42:45], v[38:41]
	s_waitcnt lgkmcnt(0)
	v_mfma_f32_16x16x32_bf16 v[10:13], v[46:49], v[42:45], v[58:61]
	ds_read_b64_tr_b16 v[20:21], v252 offset:4736
	ds_read_b64_tr_b16 v[18:19], v252 offset:128
	ds_read_b64_tr_b16 v[30:31], v252 offset:160
	ds_read_b64_tr_b16 v[32:33], v252 offset:4768
	ds_read_b64_tr_b16 v[34:35], v252 offset:192
	ds_read_b64_tr_b16 v[36:37], v252 offset:4800
	ds_read_b64_tr_b16 v[38:39], v252 offset:224
	ds_read_b64_tr_b16 v[40:41], v252 offset:4832
	s_waitcnt lgkmcnt(6)
	v_mfma_f32_16x16x32_bf16 v[18:21], v[18:21], v[42:45], v[62:65]
	s_waitcnt lgkmcnt(2)
	v_mfma_f32_16x16x32_bf16 v[34:37], v[34:37], v[42:45], v[70:73]
	v_mfma_f32_16x16x32_bf16 v[30:33], v[30:33], v[42:45], v[66:69]
	s_waitcnt lgkmcnt(0)
	v_mfma_f32_16x16x32_bf16 v[38:41], v[38:41], v[42:45], v[74:77]
	s_waitcnt lgkmcnt(0)
	s_add_i32 s5, s5, 1
	s_add_u32 s30, s30, 4
	s_addc_u32 s31, s31, 0
	s_cmp_eq_u32 s5, 8
	v_fmac_f32_e32 v118, v253, v204
	s_cbranch_scc1 .LBB0_727
	v_mov_b32_e32 v253, v118
	v_mov_b32_e32 v236, v205
	s_branch .LBB0_721
